# XCD-local seams: the leader releases the local workgroups without first waiting for its own early-issued L1 invalidate
# baseline (speedup 1.0000x reference)
; __device__ __forceinline__ unsigned xb_add(unsigned* p, unsigned v) { return __hip_atomic_fetch_add(p, v, __ATOMIC_RELAXED, __HIP_MEMORY_SCOPE_AGENT); }
; __device__ __forceinline__ void xcd_barrier(const XcdBarrier& b) {
;     ...
;             __builtin_amdgcn_fence(__ATOMIC_ACQUIRE, "agent");
;             xb_add(&bar[XB_XGEN(b.x)], 1u);
;             asm volatile("s_waitcnt vmcnt(0)" ::: "memory");
.LBB0_281:
	s_or_b64 exec, exec, s[8:9]
	s_mov_b64 s[8:9], exec
	v_mbcnt_lo_u32_b32 v0, s8, 0
	v_mbcnt_hi_u32_b32 v0, s9, v0
	v_cmp_eq_u32_e32 vcc, 0, v0
	v_readlane_b32 s101, v249, 48
	s_nop 3
	s_cmp_lg_u32 s101, 0
	s_cbranch_scc1 .Lrelw_0
	s_waitcnt vmcnt(0)
.Lrelw_0:
	s_and_saveexec_b64 s[10:11], vcc
	s_cbranch_execz .LBB0_283
	s_bcnt1_i32_b64 s3, s[8:9]
	v_mov_b32_e32 v0, 0x2000
	v_mov_b32_e32 v1, s3
	global_atomic_add v0, v1, s[6:7] offset:1024

; __device__ __forceinline__ unsigned xb_add(unsigned* p, unsigned v) { return __hip_atomic_fetch_add(p, v, __ATOMIC_RELAXED, __HIP_MEMORY_SCOPE_AGENT); }
; __device__ __forceinline__ void xcd_barrier(const XcdBarrier& b) {
;     ...
;             __builtin_amdgcn_fence(__ATOMIC_ACQUIRE, "agent");
;             xb_add(&bar[XB_XGEN(b.x)], 1u);
;             asm volatile("s_waitcnt vmcnt(0)" ::: "memory");
.LBB0_540:
	s_or_b64 exec, exec, s[10:11]
	s_mov_b64 s[10:11], exec
	v_mbcnt_lo_u32_b32 v0, s10, 0
	v_mbcnt_hi_u32_b32 v0, s11, v0
	v_cmp_eq_u32_e32 vcc, 0, v0
	v_readlane_b32 s101, v249, 48
	s_nop 3
	s_cmp_lg_u32 s101, 0
	s_cbranch_scc1 .Lrelw_2
	s_waitcnt vmcnt(0)
.Lrelw_2:
	s_and_saveexec_b64 s[12:13], vcc
	s_cbranch_execz .LBB0_542
	s_bcnt1_i32_b64 s3, s[10:11]
	v_mov_b32_e32 v0, 0x2000
	v_mov_b32_e32 v1, s3
	global_atomic_add v0, v1, s[8:9] offset:1024

; __device__ __forceinline__ unsigned xb_add(unsigned* p, unsigned v) { return __hip_atomic_fetch_add(p, v, __ATOMIC_RELAXED, __HIP_MEMORY_SCOPE_AGENT); }
; __device__ __forceinline__ void xcd_barrier(const XcdBarrier& b) {
;     ...
;             __builtin_amdgcn_fence(__ATOMIC_ACQUIRE, "agent");
;             xb_add(&bar[XB_XGEN(b.x)], 1u);
;             asm volatile("s_waitcnt vmcnt(0)" ::: "memory");
.LBB0_1503:
	s_or_b64 exec, exec, s[6:7]
	s_mov_b64 s[6:7], exec
	v_mbcnt_lo_u32_b32 v0, s6, 0
	v_mbcnt_hi_u32_b32 v0, s7, v0
	v_cmp_eq_u32_e32 vcc, 0, v0
	v_readlane_b32 s101, v249, 48
	s_nop 3
	s_cmp_lg_u32 s101, 0
	s_cbranch_scc1 .Lrelw_8
	s_waitcnt vmcnt(0)
.Lrelw_8:
	s_and_saveexec_b64 s[8:9], vcc
	s_cbranch_execz .LBB0_1505
	s_bcnt1_i32_b64 s3, s[6:7]
	v_mov_b32_e32 v0, 0x2000
	v_mov_b32_e32 v1, s3
	global_atomic_add v0, v1, s[4:5] offset:1024

; __device__ __forceinline__ unsigned xb_add(unsigned* p, unsigned v) { return __hip_atomic_fetch_add(p, v, __ATOMIC_RELAXED, __HIP_MEMORY_SCOPE_AGENT); }
; __device__ __forceinline__ void xcd_barrier(const XcdBarrier& b) {
;     ...
;             xb_add(&bar[XB_XGEN(b.x)], 1u);
.Lrelw_11:
	s_and_saveexec_b64 s[8:9], vcc
	s_cbranch_execz .LBB0_1900
	s_bcnt1_i32_b64 s6, s[6:7]
	v_mov_b32_e32 v0, 0x2000
	v_mov_b32_e32 v1, s6
	global_atomic_add v0, v1, s[4:5] offset:1024
